# v148 + small instruction cleanups: qlat accumulator zero-init as 64 v_mov_b64, SSD-conv fast path no longer computes the slow-path-only state mask
# baseline (speedup 1.0000x reference)
.LBB0_158:
	s_mov_b64 s[74:75], 0x1800
	s_min_i32 s32, s46, s42
	s_mul_hi_i32 s47, s32, 0x2aaaaaab
	s_lshr_b32 s50, s47, 31
	s_ashr_i32 s47, s47, 3
	s_add_i32 s47, s47, s50
	s_mul_i32 s50, s47, 0xffffffd0
	s_add_i32 s50, s50, s32
	s_lshl_b32 s47, s47, 6
	s_lshl_b32 s50, s50, 6
	v_or_b32_e32 v228, s50, v56
	v_mov_b32_e32 v229, 0
	v_lshl_add_u64 v[228:229], v[228:229], 1, s[6:7]
	v_add_u32_e32 v232, s47, v57
	v_mad_i64_i32 v[230:231], s[98:99], v232, s67, v[228:229]
	global_load_dwordx4 v[142:145], v[230:231], off
	v_lshl_add_u64 v[230:231], v[230:231], 0, s[74:75]
	global_load_dwordx4 v[146:149], v[230:231], off
	v_lshl_add_u64 v[230:231], v[230:231], 0, s[74:75]
	global_load_dwordx4 v[150:153], v[230:231], off
	v_lshl_add_u64 v[230:231], v[230:231], 0, s[74:75]
	global_load_dwordx4 v[162:165], v[230:231], off
	s_add_i32 s32, s46, s76
	s_min_i32 s32, s32, s42
	s_mul_hi_i32 s47, s32, 0x2aaaaaab
	s_lshr_b32 s50, s47, 31
	s_ashr_i32 s47, s47, 3
	s_add_i32 s47, s47, s50
	s_mul_i32 s50, s47, 0xffffffd0
	s_add_i32 s50, s50, s32
	s_lshl_b32 s47, s47, 6
	s_lshl_b32 s50, s50, 6
	v_or_b32_e32 v228, s50, v56
	v_mov_b32_e32 v229, 0
	v_lshl_add_u64 v[228:229], v[228:229], 1, s[6:7]
	v_add_u32_e32 v232, s47, v57
	v_mad_i64_i32 v[230:231], s[98:99], v232, s67, v[228:229]
	global_load_dwordx4 v[166:169], v[230:231], off
	v_lshl_add_u64 v[230:231], v[230:231], 0, s[74:75]
	global_load_dwordx4 v[170:173], v[230:231], off
	v_lshl_add_u64 v[230:231], v[230:231], 0, s[74:75]
	global_load_dwordx4 v[174:177], v[230:231], off
	v_lshl_add_u64 v[230:231], v[230:231], 0, s[74:75]
	global_load_dwordx4 v[178:181], v[230:231], off
	s_add_i32 s32, s46, s43
	s_min_i32 s32, s32, s42
	s_mul_hi_i32 s47, s32, 0x2aaaaaab
	s_lshr_b32 s50, s47, 31
	s_ashr_i32 s47, s47, 3
	s_add_i32 s47, s47, s50
	s_mul_i32 s50, s47, 0xffffffd0
	s_add_i32 s50, s50, s32
	s_lshl_b32 s47, s47, 6
	s_lshl_b32 s50, s50, 6
	v_or_b32_e32 v228, s50, v56
	v_mov_b32_e32 v229, 0
	v_lshl_add_u64 v[228:229], v[228:229], 1, s[6:7]
	v_add_u32_e32 v232, s47, v57
	v_mad_i64_i32 v[230:231], s[98:99], v232, s67, v[228:229]
	global_load_dwordx4 v[182:185], v[230:231], off
	v_lshl_add_u64 v[230:231], v[230:231], 0, s[74:75]
	global_load_dwordx4 v[186:189], v[230:231], off
	v_lshl_add_u64 v[230:231], v[230:231], 0, s[74:75]
	global_load_dwordx4 v[220:223], v[230:231], off
	v_lshl_add_u64 v[230:231], v[230:231], 0, s[74:75]
	global_load_dwordx4 v[224:227], v[230:231], off
	s_min_i32 s4, s46, s42
	s_mul_hi_i32 s5, s4, 0x2aaaaaab
	s_lshr_b32 s18, s5, 31
	s_ashr_i32 s5, s5, 3
	s_add_i32 s18, s5, s18
	s_mul_i32 s5, s18, 0xffffffd0
	s_lshl_b32 s19, s18, 6
	s_add_i32 s20, s5, s4
	s_add_i32 s4, s19, s92
	s_add_i32 s5, s4, 0xffff8000
	s_lshr_b32 s5, s5, 6
	s_lshl_b32 s22, s20, 6
	s_add_i32 s5, s5, 16
	s_ashr_i32 s21, s4, 11
	s_cmp_lt_i32 s4, 0x8000
	s_cselect_b32 s4, 0x7c0, 0
	s_cselect_b32 s21, s21, s5
	s_and_b32 s4, s4, s19
	s_cmp_gt_i32 s21, 15
	v_or_b32_e32 v52, s22, v56
	v_add_u32_e32 v2, s4, v54
	s_cselect_b64 s[4:5], -1, 0
	s_add_i32 s21, s21, -16
	v_ashrrev_i32_e32 v53, 31, v52
	v_cndmask_b32_e64 v0, 0, 1, s[4:5]
	s_mul_hi_u32 s25, s21, 3
	s_mul_i32 s24, s21, 3
	s_waitcnt lgkmcnt(0)
	v_lshl_add_u64 v[4:5], v[52:53], 2, s[16:17]
	v_cmp_gt_i32_e32 vcc, 3, v2
	s_cbranch_vccnz .Lssd_slow0
	s_waitcnt vmcnt(11)
	v_lshlrev_b32_e32 v38, 16, v142
	v_and_b32_e32 v106, 0xffff0000, v142
	v_lshlrev_b32_e32 v40, 16, v143
	v_and_b32_e32 v100, 0xffff0000, v143
	v_lshlrev_b32_e32 v103, 16, v144
	v_and_b32_e32 v11, 0xffff0000, v144
	v_lshlrev_b32_e32 v99, 16, v145
	v_and_b32_e32 v13, 0xffff0000, v145
	s_waitcnt vmcnt(10)
	v_lshlrev_b32_e32 v39, 16, v146
	v_and_b32_e32 v107, 0xffff0000, v146
	v_lshlrev_b32_e32 v41, 16, v147
	v_and_b32_e32 v101, 0xffff0000, v147
	v_lshlrev_b32_e32 v102, 16, v148
	v_and_b32_e32 v10, 0xffff0000, v148
	v_lshlrev_b32_e32 v98, 16, v149
	v_and_b32_e32 v12, 0xffff0000, v149
	s_waitcnt vmcnt(9)
	v_lshlrev_b32_e32 v46, 16, v150
	v_and_b32_e32 v112, 0xffff0000, v150
	v_lshlrev_b32_e32 v48, 16, v151
	v_and_b32_e32 v108, 0xffff0000, v151
	v_lshlrev_b32_e32 v111, 16, v152
	v_and_b32_e32 v43, 0xffff0000, v152
	v_lshlrev_b32_e32 v105, 16, v153
	v_and_b32_e32 v45, 0xffff0000, v153
	s_waitcnt vmcnt(8)
	v_lshlrev_b32_e32 v47, 16, v162
	v_and_b32_e32 v113, 0xffff0000, v162
	v_lshlrev_b32_e32 v49, 16, v163
	v_and_b32_e32 v109, 0xffff0000, v163
	v_lshlrev_b32_e32 v110, 16, v164
	v_and_b32_e32 v42, 0xffff0000, v164
	v_lshlrev_b32_e32 v104, 16, v165
	v_and_b32_e32 v44, 0xffff0000, v165
	s_branch .Lssd_join0
.Lssd_slow0:
	v_cmp_ne_u32_e64 s[4:5], 1, v0
	s_and_saveexec_b64 s[26:27], vcc
	s_xor_b64 s[26:27], exec, s[26:27]
	s_cbranch_execz .LBB0_161
	s_waitcnt vmcnt(0)
	v_mov_b32_e32 v13, 0
	s_and_b64 vcc, exec, s[4:5]
	v_mov_b32_e32 v99, 0
	v_mov_b32_e32 v11, 0
	v_mov_b32_e32 v103, 0
	v_mov_b32_e32 v100, 0
	v_mov_b32_e32 v40, 0
	v_mov_b32_e32 v106, 0
	v_mov_b32_e32 v38, 0
	s_cbranch_vccnz .LBB0_161
	v_ashrrev_i32_e32 v3, 31, v2
	v_lshl_add_u64 v[6:7], s[24:25], 0, v[2:3]
	v_mad_u64_u32 v[8:9], s[28:29], v6, s86, v[4:5]
	v_mad_i32_i24 v9, v7, s86, v9
	global_load_dwordx4 v[10:13], v[8:9], off offset:16
	global_load_dwordx4 v[38:41], v[8:9], off
	s_waitcnt vmcnt(1)
	v_mov_b32_e32 v99, v12
	v_mov_b32_e32 v103, v10
	s_waitcnt vmcnt(0)
	v_mov_b32_e32 v100, v41
	v_mov_b32_e32 v106, v39

.Lssd_join0:
	s_add_i32 s21, s76, s46
	s_min_i32 s4, s21, s42
	s_mul_hi_i32 s5, s4, 0x2aaaaaab
	s_lshr_b32 s23, s5, 31
	s_ashr_i32 s5, s5, 3
	s_add_i32 s24, s5, s23
	s_mul_i32 s5, s24, 0xffffffd0
	s_lshl_b32 s25, s24, 6
	s_add_i32 s26, s5, s4
	s_add_i32 s4, s25, s92
	s_add_i32 s5, s4, 0xffff8000
	s_lshr_b32 s5, s5, 6
	s_lshl_b32 s28, s26, 6
	s_add_i32 s5, s5, 16
	s_ashr_i32 s23, s4, 11
	s_cmp_lt_i32 s4, 0x8000
	s_cselect_b32 s4, 0x7c0, 0
	s_cselect_b32 s23, s23, s5
	s_and_b32 s4, s4, s25
	s_cmp_gt_i32 s23, 15
	v_or_b32_e32 v50, s28, v56
	v_add_u32_e32 v2, s4, v54
	s_cselect_b64 s[4:5], -1, 0
	s_add_i32 s23, s23, -16
	v_ashrrev_i32_e32 v51, 31, v50
	v_cndmask_b32_e64 v0, 0, 1, s[4:5]
	s_mul_hi_u32 s31, s23, 3
	s_mul_i32 s30, s23, 3
	v_lshl_add_u64 v[4:5], v[50:51], 2, s[16:17]
	v_cmp_gt_i32_e32 vcc, 3, v2
	s_cbranch_vccnz .Lssd_slow1
	s_waitcnt vmcnt(7)
	v_lshlrev_b32_e32 v34, 16, v166
	v_and_b32_e32 v96, 0xffff0000, v166
	v_lshlrev_b32_e32 v36, 16, v167
	v_and_b32_e32 v92, 0xffff0000, v167
	v_lshlrev_b32_e32 v95, 16, v168
	v_and_b32_e32 v31, 0xffff0000, v168
	v_lshlrev_b32_e32 v91, 16, v169
	v_and_b32_e32 v33, 0xffff0000, v169
	s_waitcnt vmcnt(6)
	v_lshlrev_b32_e32 v35, 16, v170
	v_and_b32_e32 v97, 0xffff0000, v170
	v_lshlrev_b32_e32 v37, 16, v171
	v_and_b32_e32 v93, 0xffff0000, v171
	v_lshlrev_b32_e32 v94, 16, v172
	v_and_b32_e32 v30, 0xffff0000, v172
	v_lshlrev_b32_e32 v90, 16, v173
	v_and_b32_e32 v32, 0xffff0000, v173
	s_waitcnt vmcnt(5)
	v_lshlrev_b32_e32 v26, 16, v174
	v_and_b32_e32 v86, 0xffff0000, v174
	v_lshlrev_b32_e32 v28, 16, v175
	v_and_b32_e32 v84, 0xffff0000, v175
	v_lshlrev_b32_e32 v89, 16, v176
	v_and_b32_e32 v23, 0xffff0000, v176
	v_lshlrev_b32_e32 v83, 16, v177
	v_and_b32_e32 v25, 0xffff0000, v177
	s_waitcnt vmcnt(4)
	v_lshlrev_b32_e32 v27, 16, v178
	v_and_b32_e32 v87, 0xffff0000, v178
	v_lshlrev_b32_e32 v29, 16, v179
	v_and_b32_e32 v85, 0xffff0000, v179
	v_lshlrev_b32_e32 v88, 16, v180
	v_and_b32_e32 v22, 0xffff0000, v180
	v_lshlrev_b32_e32 v82, 16, v181
	v_and_b32_e32 v24, 0xffff0000, v181
	s_branch .Lssd_join1
.Lssd_slow1:
	v_cmp_ne_u32_e64 s[4:5], 1, v0
	s_and_saveexec_b64 s[34:35], vcc
	s_xor_b64 s[34:35], exec, s[34:35]
	s_cbranch_execz .LBB0_183
	v_mov_b32_e32 v33, 0
	s_and_b64 vcc, exec, s[4:5]
	v_mov_b32_e32 v91, 0
	v_mov_b32_e32 v31, 0
	v_mov_b32_e32 v95, 0
	v_mov_b32_e32 v92, 0
	v_mov_b32_e32 v36, 0
	v_mov_b32_e32 v96, 0
	v_mov_b32_e32 v34, 0
	s_cbranch_vccnz .LBB0_183
	v_ashrrev_i32_e32 v3, 31, v2
	v_lshl_add_u64 v[6:7], s[30:31], 0, v[2:3]
	v_mad_u64_u32 v[8:9], s[36:37], v6, s86, v[4:5]
	v_mad_i32_i24 v9, v7, s86, v9
	global_load_dwordx4 v[30:33], v[8:9], off offset:16
	global_load_dwordx4 v[34:37], v[8:9], off
	s_waitcnt vmcnt(1)
	v_mov_b32_e32 v91, v32
	v_mov_b32_e32 v95, v30
	s_waitcnt vmcnt(0)
	v_mov_b32_e32 v92, v37
	v_mov_b32_e32 v96, v35

.Lssd_join1:
	s_add_i32 s27, s43, s46
	s_min_i32 s4, s27, s42
	s_mul_hi_i32 s5, s4, 0x2aaaaaab
	s_lshr_b32 s23, s5, 31
	s_ashr_i32 s5, s5, 3
	s_add_i32 s30, s5, s23
	s_mul_i32 s5, s30, 0xffffffd0
	s_lshl_b32 s31, s30, 6
	s_add_i32 s34, s5, s4
	s_add_i32 s4, s31, s92
	s_add_i32 s5, s4, 0xffff8000
	s_lshr_b32 s5, s5, 6
	s_lshl_b32 s36, s34, 6
	s_add_i32 s5, s5, 16
	s_ashr_i32 s23, s4, 11
	s_cmp_lt_i32 s4, 0x8000
	s_cselect_b32 s4, 0x7c0, 0
	s_cselect_b32 s23, s23, s5
	s_and_b32 s4, s4, s31
	s_cmp_gt_i32 s23, 15
	v_or_b32_e32 v76, s36, v56
	v_add_u32_e32 v114, s4, v54
	s_cselect_b64 s[4:5], -1, 0
	s_add_i32 s23, s23, -16
	v_ashrrev_i32_e32 v77, 31, v76
	v_cndmask_b32_e64 v0, 0, 1, s[4:5]
	s_mul_hi_u32 s39, s23, 3
	s_mul_i32 s38, s23, 3
	v_lshl_add_u64 v[116:117], v[76:77], 2, s[16:17]
	v_cmp_gt_i32_e32 vcc, 3, v114
	s_cbranch_vccnz .Lssd_slow2
	s_waitcnt vmcnt(3)
	v_lshlrev_b32_e32 v18, 16, v182
	v_and_b32_e32 v80, 0xffff0000, v182
	v_lshlrev_b32_e32 v20, 16, v183
	v_and_b32_e32 v74, 0xffff0000, v183
	v_lshlrev_b32_e32 v79, 16, v184
	v_and_b32_e32 v15, 0xffff0000, v184
	v_lshlrev_b32_e32 v73, 16, v185
	v_and_b32_e32 v17, 0xffff0000, v185
	s_waitcnt vmcnt(2)
	v_lshlrev_b32_e32 v19, 16, v186
	v_and_b32_e32 v81, 0xffff0000, v186
	v_lshlrev_b32_e32 v21, 16, v187
	v_and_b32_e32 v75, 0xffff0000, v187
	v_lshlrev_b32_e32 v78, 16, v188
	v_and_b32_e32 v14, 0xffff0000, v188
	v_lshlrev_b32_e32 v72, 16, v189
	v_and_b32_e32 v16, 0xffff0000, v189
	s_waitcnt vmcnt(1)
	v_lshlrev_b32_e32 v6, 16, v220
	v_and_b32_e32 v68, 0xffff0000, v220
	v_lshlrev_b32_e32 v8, 16, v221
	v_and_b32_e32 v64, 0xffff0000, v221
	v_lshlrev_b32_e32 v71, 16, v222
	v_and_b32_e32 v3, 0xffff0000, v222
	v_lshlrev_b32_e32 v67, 16, v223
	v_and_b32_e32 v5, 0xffff0000, v223
	s_waitcnt vmcnt(0)
	v_lshlrev_b32_e32 v7, 16, v224
	v_and_b32_e32 v69, 0xffff0000, v224
	v_lshlrev_b32_e32 v9, 16, v225
	v_and_b32_e32 v65, 0xffff0000, v225
	v_lshlrev_b32_e32 v70, 16, v226
	v_and_b32_e32 v2, 0xffff0000, v226
	v_lshlrev_b32_e32 v66, 16, v227
	v_and_b32_e32 v4, 0xffff0000, v227
	s_branch .Lssd_join2
.Lssd_slow2:
	v_cmp_ne_u32_e64 s[4:5], 1, v0
	s_and_saveexec_b64 s[40:41], vcc
	s_xor_b64 s[40:41], exec, s[40:41]
	s_cbranch_execz .LBB0_205
	v_mov_b32_e32 v17, 0
	s_and_b64 vcc, exec, s[4:5]
	v_mov_b32_e32 v73, 0
	v_mov_b32_e32 v15, 0
	v_mov_b32_e32 v79, 0
	v_mov_b32_e32 v74, 0
	v_mov_b32_e32 v20, 0
	v_mov_b32_e32 v80, 0
	v_mov_b32_e32 v18, 0
	s_cbranch_vccnz .LBB0_205
	v_ashrrev_i32_e32 v115, 31, v114
	v_lshl_add_u64 v[2:3], s[38:39], 0, v[114:115]
	v_mad_u64_u32 v[4:5], s[48:49], v2, s86, v[116:117]
	v_mad_i32_i24 v5, v3, s86, v5
	global_load_dwordx4 v[14:17], v[4:5], off offset:16
	global_load_dwordx4 v[18:21], v[4:5], off
	s_waitcnt vmcnt(1)
	v_mov_b32_e32 v73, v16
	v_mov_b32_e32 v79, v14
	s_waitcnt vmcnt(0)
	v_mov_b32_e32 v74, v21
	v_mov_b32_e32 v80, v19

.LBB0_428:
	s_ashr_i32 s27, s26, 31
	s_ashr_i32 s25, s24, 31
	s_lshl_b64 s[8:9], s[26:27], 20
	s_lshl_b64 s[28:29], s[24:25], 8
	s_add_u32 s8, s3, s8
	s_addc_u32 s9, s42, s9
	s_add_u32 s28, s8, s28
	s_addc_u32 s29, s9, s29
	s_lshl_b64 s[8:9], s[24:25], 16
	v_readlane_b32 s25, v255, 47
	s_add_u32 s30, s25, s8
	v_readlane_b32 s8, v255, 48
	s_addc_u32 s31, s8, s9
	v_mov_b64_e32 v[2:3], 0
	v_mov_b64_e32 v[4:5], 0
	v_mov_b64_e32 v[6:7], 0
	v_mov_b64_e32 v[8:9], 0
	v_mov_b64_e32 v[10:11], 0
	v_mov_b64_e32 v[12:13], 0
	v_mov_b64_e32 v[14:15], 0
	v_mov_b64_e32 v[16:17], 0
	v_mov_b64_e32 v[22:23], 0
	v_mov_b64_e32 v[24:25], 0
	v_mov_b64_e32 v[30:31], 0
	v_mov_b64_e32 v[32:33], 0
	v_mov_b64_e32 v[34:35], 0
	v_mov_b64_e32 v[36:37], 0
	v_mov_b64_e32 v[38:39], 0
	v_mov_b64_e32 v[40:41], 0
	v_mov_b64_e32 v[42:43], 0
	v_mov_b64_e32 v[44:45], 0
	v_mov_b64_e32 v[46:47], 0
	v_mov_b64_e32 v[48:49], 0
	v_mov_b64_e32 v[50:51], 0
	v_mov_b64_e32 v[52:53], 0
	v_mov_b64_e32 v[54:55], 0
	v_mov_b64_e32 v[56:57], 0
	v_mov_b64_e32 v[58:59], 0
	v_mov_b64_e32 v[60:61], 0
	v_mov_b64_e32 v[62:63], 0
	v_mov_b64_e32 v[64:65], 0
	v_mov_b64_e32 v[66:67], 0
	v_mov_b64_e32 v[68:69], 0
	v_mov_b64_e32 v[70:71], 0
	v_mov_b64_e32 v[72:73], 0
	v_mov_b64_e32 v[74:75], 0
	v_mov_b64_e32 v[76:77], 0
	v_mov_b64_e32 v[78:79], 0
	v_mov_b64_e32 v[80:81], 0
	v_mov_b64_e32 v[82:83], 0
	v_mov_b64_e32 v[84:85], 0
	v_mov_b64_e32 v[86:87], 0
	v_mov_b64_e32 v[88:89], 0
	v_mov_b64_e32 v[90:91], 0
	v_mov_b64_e32 v[92:93], 0
	v_mov_b64_e32 v[94:95], 0
	v_mov_b64_e32 v[96:97], 0
	v_mov_b64_e32 v[98:99], 0
	v_mov_b64_e32 v[100:101], 0
	v_mov_b64_e32 v[102:103], 0
	v_mov_b64_e32 v[104:105], 0
	v_mov_b64_e32 v[106:107], 0
	v_mov_b64_e32 v[108:109], 0
	v_mov_b64_e32 v[110:111], 0
	v_mov_b64_e32 v[112:113], 0
	v_mov_b64_e32 v[114:115], 0
	v_mov_b64_e32 v[116:117], 0
	v_mov_b64_e32 v[118:119], 0
	v_mov_b64_e32 v[120:121], 0
	v_mov_b64_e32 v[122:123], 0
	v_mov_b64_e32 v[124:125], 0
	v_mov_b64_e32 v[126:127], 0
	v_mov_b64_e32 v[128:129], 0
	v_mov_b64_e32 v[140:141], 0
	v_mov_b64_e32 v[142:143], 0
	v_mov_b64_e32 v[144:145], 0
	v_mov_b64_e32 v[146:147], 0
	s_andn2_b64 vcc, exec, s[18:19]
	s_cbranch_vccnz .LBB0_432
	s_and_b64 s[8:9], s[4:5], exec
	s_cselect_b32 s25, s29, s35
	s_cselect_b32 s27, s28, s34
	s_cselect_b32 s79, s31, s37
	s_cselect_b32 s91, s30, s36
	s_add_u32 s34, s34, 0x80080
	s_addc_u32 s35, s35, 0
	s_add_u32 vcc_lo, s36, 0x100
	s_addc_u32 vcc_hi, s37, 0
	s_mov_b32 s36, 0
	v_mov_b64_e32 v[2:3], 0
	v_mov_b64_e32 v[4:5], 0
	v_mov_b64_e32 v[6:7], 0
	v_mov_b64_e32 v[8:9], 0
	v_mov_b64_e32 v[10:11], 0
	v_mov_b64_e32 v[12:13], 0
	v_mov_b64_e32 v[14:15], 0
	v_mov_b64_e32 v[16:17], 0
	v_mov_b64_e32 v[18:19], 0
	v_mov_b64_e32 v[20:21], 0
	v_mov_b64_e32 v[22:23], 0
	v_mov_b64_e32 v[24:25], 0
	v_mov_b64_e32 v[26:27], 0
	v_mov_b64_e32 v[28:29], 0
	v_mov_b64_e32 v[30:31], 0
	v_mov_b64_e32 v[32:33], 0
	v_mov_b64_e32 v[34:35], 0
	v_mov_b64_e32 v[36:37], 0
	v_mov_b64_e32 v[38:39], 0
	v_mov_b64_e32 v[40:41], 0
	v_mov_b64_e32 v[42:43], 0
	v_mov_b64_e32 v[44:45], 0
	v_mov_b64_e32 v[46:47], 0
	v_mov_b64_e32 v[48:49], 0
	v_mov_b64_e32 v[50:51], 0
	v_mov_b64_e32 v[52:53], 0
	v_mov_b64_e32 v[54:55], 0
	v_mov_b64_e32 v[56:57], 0
	v_mov_b64_e32 v[58:59], 0
	v_mov_b64_e32 v[60:61], 0
	v_mov_b64_e32 v[62:63], 0
	v_mov_b64_e32 v[64:65], 0
	v_mov_b64_e32 v[66:67], 0
	v_mov_b64_e32 v[68:69], 0
	v_mov_b64_e32 v[70:71], 0
	v_mov_b64_e32 v[72:73], 0
	v_mov_b64_e32 v[74:75], 0
	v_mov_b64_e32 v[76:77], 0
	v_mov_b64_e32 v[78:79], 0
	v_mov_b64_e32 v[80:81], 0
	v_mov_b64_e32 v[82:83], 0
	v_mov_b64_e32 v[84:85], 0
	v_mov_b64_e32 v[86:87], 0
	v_mov_b64_e32 v[88:89], 0
	v_mov_b64_e32 v[90:91], 0
	v_mov_b64_e32 v[92:93], 0
	v_mov_b64_e32 v[94:95], 0
	v_mov_b64_e32 v[96:97], 0
	v_mov_b64_e32 v[98:99], 0
	v_mov_b64_e32 v[100:101], 0
	v_mov_b64_e32 v[102:103], 0
	v_mov_b64_e32 v[104:105], 0
	v_mov_b64_e32 v[106:107], 0
	v_mov_b64_e32 v[108:109], 0
	v_mov_b64_e32 v[110:111], 0
	v_mov_b64_e32 v[112:113], 0
	v_mov_b64_e32 v[114:115], 0
	v_mov_b64_e32 v[116:117], 0
	v_mov_b64_e32 v[118:119], 0
	v_mov_b64_e32 v[120:121], 0
	v_mov_b64_e32 v[122:123], 0
	v_mov_b64_e32 v[124:125], 0
	v_mov_b64_e32 v[126:127], 0
	v_mov_b64_e32 v[128:129], 0
